# conv preheader: FIR weights, LN gain/bias and the first tile's rows all in flight together (two cold round trips removed per layer)
# speedup vs baseline: 1.0049x; 1.0049x over previous
.LBB7_803:
	s_or_b64 exec, exec, s[6:7]
	v_readlane_b32 s4, v252, 7
	v_readlane_b32 s5, v252, 8
	s_andn2_b64 vcc, exec, s[4:5]
	s_cbranch_vccnz .LBB7_813
	s_load_dwordx8 s[12:19], s[42:43], 0xa0
	v_readlane_b32 s4, v250, 10
	v_readlane_b32 s5, v250, 11
	s_lshl_b64 s[4:5], s[4:5], 2
	v_readlane_b32 s3, v250, 27
	s_waitcnt lgkmcnt(0)
	s_add_u32 s6, s18, s4
	s_addc_u32 s7, s19, s5
	s_add_u32 s8, s16, s4
	s_addc_u32 s9, s17, s5
	s_add_u32 s12, s12, s3
	s_movk_i32 s3, 0xba0
	s_addc_u32 s13, s13, 0
	v_cmp_gt_i32_e32 vcc, s3, v150
	s_movk_i32 s3, 0x180
	s_add_u32 s4, s14, s4
	v_cmp_gt_i32_e64 s[40:41], s3, v150
	v_ashrrev_i32_e32 v151, 31, v150
	v_lshlrev_b32_e32 v0, 2, v150
	v_readlane_b32 s3, v253, 39
	s_addc_u32 s5, s15, s5
	v_lshlrev_b64 v[2:3], 2, v[150:151]
	v_add_u32_e32 v108, 0, v0
	v_add_u32_e32 v109, s3, v0
	v_mov_b32_e32 v0, s3
	v_lshl_add_u64 v[10:11], s[4:5], 0, v[2:3]
	v_mad_u64_u32 v[12:13], s[4:5], v204, 24, v[0:1]
	v_lshl_add_u64 v[14:15], s[12:13], 0, v[2:3]
	s_mov_b64 s[4:5], 0x1200
	v_lshl_add_u64 v[16:17], v[14:15], 0, s[4:5]
	s_mov_b64 s[4:5], 0x1800
	v_lshl_add_u64 v[18:19], v[14:15], 0, s[4:5]
	s_mov_b64 s[4:5], 0x1e00
	v_lshl_add_u64 v[20:21], v[14:15], 0, s[4:5]
	s_mov_b64 s[4:5], 0x2400
	v_lshl_add_u64 v[22:23], v[14:15], 0, s[4:5]
	s_mov_b64 s[4:5], 0x2a00
	v_lshl_add_u64 v[24:25], v[14:15], 0, s[4:5]
	s_mov_b64 s[4:5], 0x3000
	v_lshl_add_u64 v[26:27], v[14:15], 0, s[4:5]
	s_mov_b64 s[4:5], 0x3600
	v_and_b32_e32 v0, 64, v163
	v_lshl_add_u64 v[28:29], v[14:15], 0, s[4:5]
	s_mov_b64 s[4:5], 0x3c00
	v_add_u32_e32 v0, 64, v0
	v_xor_b32_e32 v4, 1, v163
	v_lshl_add_u64 v[30:31], v[14:15], 0, s[4:5]
	s_mov_b64 s[4:5], 0x4200
	v_cmp_lt_i32_e64 s[42:43], v4, v0
	v_lshl_add_u64 v[32:33], v[14:15], 0, s[4:5]
	s_mov_b64 s[4:5], 0x4800
	v_cndmask_b32_e64 v4, v163, v4, s[42:43]
	v_lshl_add_u64 v[34:35], v[14:15], 0, s[4:5]
	s_mov_b64 s[4:5], 0x4e00
	v_lshlrev_b32_e32 v13, 2, v4
	v_xor_b32_e32 v4, 2, v163
	v_lshl_add_u64 v[36:37], v[14:15], 0, s[4:5]
	s_mov_b64 s[4:5], 0x5400
	v_cmp_lt_i32_e64 s[42:43], v4, v0
	v_lshl_add_u64 v[38:39], v[14:15], 0, s[4:5]
	s_mov_b64 s[4:5], 0x5a00
	v_cndmask_b32_e64 v4, v163, v4, s[42:43]
	v_lshl_add_u64 v[40:41], v[14:15], 0, s[4:5]
	s_mov_b64 s[4:5], 0x6000
	v_lshlrev_b32_e32 v110, 2, v4
	v_xor_b32_e32 v4, 4, v163
	v_lshl_add_u64 v[42:43], v[14:15], 0, s[4:5]
	s_mov_b64 s[4:5], 0x6600
	v_cmp_lt_i32_e64 s[42:43], v4, v0
	v_lshl_add_u64 v[44:45], v[14:15], 0, s[4:5]
	s_mov_b64 s[4:5], 0x6c00
	v_cndmask_b32_e64 v4, v163, v4, s[42:43]
	v_lshl_add_u64 v[46:47], v[14:15], 0, s[4:5]
	s_mov_b64 s[4:5], 0x7200
	v_lshlrev_b32_e32 v111, 2, v4
	v_xor_b32_e32 v4, 8, v163
	v_lshl_add_u64 v[48:49], v[14:15], 0, s[4:5]
	s_mov_b64 s[4:5], 0x7800
	v_cmp_lt_i32_e64 s[42:43], v4, v0
	v_lshl_add_u64 v[50:51], v[14:15], 0, s[4:5]
	s_mov_b64 s[4:5], 0x7e00
	v_cndmask_b32_e64 v4, v163, v4, s[42:43]
	v_lshl_add_u64 v[52:53], v[14:15], 0, s[4:5]
	s_mov_b64 s[4:5], 0x8400
	v_lshlrev_b32_e32 v112, 2, v4
	v_xor_b32_e32 v4, 16, v163
	v_lshl_add_u64 v[54:55], v[14:15], 0, s[4:5]
	s_mov_b64 s[4:5], 0x8a00
	v_cmp_lt_i32_e64 s[42:43], v4, v0
	v_lshl_add_u64 v[56:57], v[14:15], 0, s[4:5]
	s_mov_b64 s[4:5], 0x9000
	v_cndmask_b32_e64 v4, v163, v4, s[42:43]
	v_lshl_add_u64 v[58:59], v[14:15], 0, s[4:5]
	s_mov_b64 s[4:5], 0x9600
	v_lshlrev_b32_e32 v113, 2, v4
	v_xor_b32_e32 v4, 32, v163
	v_lshl_add_u64 v[60:61], v[14:15], 0, s[4:5]
	s_mov_b64 s[4:5], 0x9c00
	v_cmp_lt_i32_e64 s[42:43], v4, v0
	v_lshl_add_u64 v[62:63], v[14:15], 0, s[4:5]
	s_mov_b64 s[4:5], 0xa200
	v_cndmask_b32_e64 v0, v163, v4, s[42:43]
	v_mul_lo_u32 v4, v204, 6
	v_lshl_add_u64 v[64:65], v[14:15], 0, s[4:5]
	s_mov_b64 s[4:5], 0xa800
	v_ashrrev_i32_e32 v5, 31, v4
	v_lshl_add_u64 v[66:67], v[14:15], 0, s[4:5]
	s_mov_b64 s[4:5], 0xae00
	v_lshl_add_u64 v[68:69], v[14:15], 0, s[4:5]
	s_mov_b64 s[4:5], 0xb400
	v_lshlrev_b64 v[2:3], 2, v[4:5]
	v_lshlrev_b32_e32 v114, 2, v0
	v_lshl_add_u64 v[70:71], v[14:15], 0, s[4:5]
	v_add_u32_e32 v115, 0x10200, v108
	v_add_u32_e32 v116, 0x10800, v108
	v_add_u32_e32 v117, 0x10e00, v108
	v_add_u32_e32 v118, 0x11400, v108
	v_add_u32_e32 v119, 0x11a00, v108
	v_add_u32_e32 v120, 0x12000, v108
	v_add_u32_e32 v121, 0x12600, v108
	v_add_u32_e32 v122, 0x12c00, v108
	v_add_u32_e32 v123, 0x13200, v108
	v_add_u32_e32 v124, 0x13800, v108
	v_add_u32_e32 v125, 0x13e00, v108
	v_add_u32_e32 v126, 0x14400, v108
	v_add_u32_e32 v127, 0x14a00, v108
	v_add_u32_e32 v128, 0x15000, v108
	v_add_u32_e32 v129, 0x15600, v108
	v_add_u32_e32 v130, 0x15c00, v108
	v_add_u32_e32 v131, 0x16200, v108
	v_add_u32_e32 v132, 0x16800, v108
	v_add_u32_e32 v133, 0x16e00, v108
	v_lshl_add_u64 v[72:73], s[8:9], 0, v[2:3]
	v_lshl_add_u64 v[74:75], s[6:7], 0, v[2:3]
	v_lshl_add_u64 v[76:77], v[4:5], 1, s[0:1]
	s_and_saveexec_b64 s[4:5], s[40:41]
	global_load_dword v247, v[10:11], off
	global_load_dword v216, v[14:15], off
	global_load_dword v217, v[14:15], off offset:1536
	global_load_dword v218, v[14:15], off offset:3072
	global_load_dword v219, v[16:17], off
	global_load_dword v220, v[18:19], off
	global_load_dword v221, v[20:21], off
	global_load_dword v222, v[22:23], off
	global_load_dword v223, v[24:25], off
	global_load_dword v224, v[26:27], off
	global_load_dword v225, v[28:29], off
	global_load_dword v226, v[30:31], off
	global_load_dword v227, v[32:33], off
	global_load_dword v228, v[34:35], off
	global_load_dword v229, v[36:37], off
	global_load_dword v230, v[38:39], off
	global_load_dword v231, v[40:41], off
	global_load_dword v232, v[42:43], off
	global_load_dword v233, v[44:45], off
	global_load_dword v234, v[46:47], off
	global_load_dword v235, v[48:49], off
	global_load_dword v236, v[50:51], off
	global_load_dword v237, v[52:53], off
	global_load_dword v238, v[54:55], off
	global_load_dword v239, v[56:57], off
	global_load_dword v240, v[58:59], off
	global_load_dword v241, v[60:61], off
	global_load_dword v242, v[62:63], off
	global_load_dword v243, v[64:65], off
	global_load_dword v244, v[66:67], off
	global_load_dword v245, v[68:69], off
	global_load_dword v246, v[70:71], off
	s_or_b64 exec, exec, s[4:5]
	global_load_dwordx4 v[14:17], v[72:73], off
	global_load_dwordx2 v[18:19], v[72:73], off offset:16
	global_load_dwordx4 v[20:23], v[74:75], off
	global_load_dwordx2 v[10:11], v[74:75], off offset:16
	s_mov_b32 s12, s2
	s_movk_i32 s14, 0x1a0
	v_cmp_gt_i32_e64 s[6:7], s14, v150
	s_lshl_b32 s15, s12, 5
	s_and_b32 s3, s15, 0x7e0
	s_sub_i32 s3, 29, s3
	s_sub_i32 s4, s15, 30
	s_mov_b32 s5, 0x2aaaaaab
	s_movk_i32 s14, 0xfe80
	v_mov_b32_e32 v79, v150
	v_mul_hi_i32 v80, v79, s5
	v_lshrrev_b32_e32 v81, 31, v80
	v_ashrrev_i32_e32 v80, 3, v80
	v_add_u32_e32 v80, v80, v81
	v_cmp_lt_i32_e64 s[42:43], s3, v80
	s_nop 1
	s_and_saveexec_b64 s[8:9], s[42:43]
	v_add_u32_e32 v82, s4, v80
	v_ashrrev_i32_e32 v83, 31, v82
	v_lshlrev_b64 v[82:83], 11, v[82:83]
	v_lshl_add_u64 v[82:83], s[44:45], 0, v[82:83]
	v_lshlrev_b32_e32 v84, 3, v79
	v_mad_i32_i24 v84, v80, s14, v84
	v_mov_b32_e32 v85, 0
	v_lshl_add_u64 v[82:83], v[84:85], 1, v[82:83]
	global_load_dwordx4 v[24:27], v[82:83], off offset:512
	global_load_dwordx4 v[28:31], v[82:83], off offset:1280
	s_or_b64 exec, exec, s[8:9]
	v_add_u32_e32 v79, 512, v150
	v_mul_hi_i32 v80, v79, s5
	v_lshrrev_b32_e32 v81, 31, v80
	v_ashrrev_i32_e32 v80, 3, v80
	v_add_u32_e32 v80, v80, v81
	v_cmp_lt_i32_e64 s[42:43], s3, v80
	s_nop 1
	s_and_saveexec_b64 s[8:9], s[42:43]
	v_add_u32_e32 v82, s4, v80
	v_ashrrev_i32_e32 v83, 31, v82
	v_lshlrev_b64 v[82:83], 11, v[82:83]
	v_lshl_add_u64 v[82:83], s[44:45], 0, v[82:83]
	v_lshlrev_b32_e32 v84, 3, v79
	v_mad_i32_i24 v84, v80, s14, v84
	v_mov_b32_e32 v85, 0
	v_lshl_add_u64 v[82:83], v[84:85], 1, v[82:83]
	global_load_dwordx4 v[32:35], v[82:83], off offset:512
	global_load_dwordx4 v[36:39], v[82:83], off offset:1280
	s_or_b64 exec, exec, s[8:9]
	v_add_u32_e32 v79, 1024, v150
	v_mul_hi_i32 v80, v79, s5
	v_lshrrev_b32_e32 v81, 31, v80
	v_ashrrev_i32_e32 v80, 3, v80
	v_add_u32_e32 v80, v80, v81
	v_cmp_lt_i32_e64 s[42:43], s3, v80
	s_nop 1
	s_and_saveexec_b64 s[8:9], s[42:43]
	v_add_u32_e32 v82, s4, v80
	v_ashrrev_i32_e32 v83, 31, v82
	v_lshlrev_b64 v[82:83], 11, v[82:83]
	v_lshl_add_u64 v[82:83], s[44:45], 0, v[82:83]
	v_lshlrev_b32_e32 v84, 3, v79
	v_mad_i32_i24 v84, v80, s14, v84
	v_mov_b32_e32 v85, 0
	v_lshl_add_u64 v[82:83], v[84:85], 1, v[82:83]
	global_load_dwordx4 v[40:43], v[82:83], off offset:512
	global_load_dwordx4 v[44:47], v[82:83], off offset:1280
	s_or_b64 exec, exec, s[8:9]
	v_add_u32_e32 v79, 1536, v150
	v_mul_hi_i32 v80, v79, s5
	v_lshrrev_b32_e32 v81, 31, v80
	v_ashrrev_i32_e32 v80, 3, v80
	v_add_u32_e32 v80, v80, v81
	v_cmp_lt_i32_e64 s[42:43], s3, v80
	s_nop 1
	s_and_saveexec_b64 s[8:9], s[42:43]
	v_add_u32_e32 v82, s4, v80
	v_ashrrev_i32_e32 v83, 31, v82
	v_lshlrev_b64 v[82:83], 11, v[82:83]
	v_lshl_add_u64 v[82:83], s[44:45], 0, v[82:83]
	v_lshlrev_b32_e32 v84, 3, v79
	v_mad_i32_i24 v84, v80, s14, v84
	v_mov_b32_e32 v85, 0
	v_lshl_add_u64 v[82:83], v[84:85], 1, v[82:83]
	global_load_dwordx4 v[48:51], v[82:83], off offset:512
	global_load_dwordx4 v[52:55], v[82:83], off offset:1280
	s_or_b64 exec, exec, s[8:9]
	v_add_u32_e32 v79, 2048, v150
	v_mul_hi_i32 v80, v79, s5
	v_lshrrev_b32_e32 v81, 31, v80
	v_ashrrev_i32_e32 v80, 3, v80
	v_add_u32_e32 v80, v80, v81
	v_cmp_lt_i32_e64 s[42:43], s3, v80
	s_nop 1
	s_and_saveexec_b64 s[8:9], s[42:43]
	v_add_u32_e32 v82, s4, v80
	v_ashrrev_i32_e32 v83, 31, v82
	v_lshlrev_b64 v[82:83], 11, v[82:83]
	v_lshl_add_u64 v[82:83], s[44:45], 0, v[82:83]
	v_lshlrev_b32_e32 v84, 3, v79
	v_mad_i32_i24 v84, v80, s14, v84
	v_mov_b32_e32 v85, 0
	v_lshl_add_u64 v[82:83], v[84:85], 1, v[82:83]
	global_load_dwordx4 v[56:59], v[82:83], off offset:512
	global_load_dwordx4 v[60:63], v[82:83], off offset:1280
	s_or_b64 exec, exec, s[8:9]
	v_add_u32_e32 v79, 2560, v150
	v_mul_hi_i32 v80, v79, s5
	v_lshrrev_b32_e32 v81, 31, v80
	v_ashrrev_i32_e32 v80, 3, v80
	v_add_u32_e32 v80, v80, v81
	v_cmp_lt_i32_e64 s[42:43], s3, v80
	s_nop 1
	s_and_b64 s[42:43], s[42:43], s[6:7]
	s_and_saveexec_b64 s[8:9], s[42:43]
	v_add_u32_e32 v82, s4, v80
	v_ashrrev_i32_e32 v83, 31, v82
	v_lshlrev_b64 v[82:83], 11, v[82:83]
	v_lshl_add_u64 v[82:83], s[44:45], 0, v[82:83]
	v_lshlrev_b32_e32 v84, 3, v79
	v_mad_i32_i24 v84, v80, s14, v84
	v_mov_b32_e32 v85, 0
	v_lshl_add_u64 v[82:83], v[84:85], 1, v[82:83]
	global_load_dwordx4 v[64:67], v[82:83], off offset:512
	global_load_dwordx4 v[68:71], v[82:83], off offset:1280
	s_or_b64 exec, exec, s[8:9]
	s_branch .LBB7_806
